# attention loop: score rescale+exp VALU block executed before the WAR barrier (both half-iterations) so it overlaps other waves' PV
# baseline (speedup 1.0000x reference)
; #define SBAR() __builtin_amdgcn_sched_barrier(0)
; #define SLOAD(i, k0) do { sr_[i].vs0 = St::ld8(&Vh[(long)((k0) + sr) * LDK + sc]); sr_[i].vs1 = St::ld8(&Vh[(long)((k0) + 32 + sr) * LDK + sc]); \
;     sr_[i].ks0 = St::ld8(&Kh[(long)((k0) + sr) * LDK + sc]); sr_[i].ks1 = St::ld8(&Kh[(long)((k0) + 32 + sr) * LDK + sc]); } while (0)
; __device__ __forceinline__ void attn_unit(const bf16* Qb, const bf16* __restrict__ Kh, const bf16* __restrict__ Vh, bf16* Ob, int seq, char* lds,
;                                           const float* __restrict__ rope, const float* __restrict__ qg, const int mk_wid) {
;     ...
;     SBAR(); qkt(pB0, pB1, (bf16*)((char*)K_lds + SHM_K), qr, r32, hi);
;     finishSM(pA0, pA1, alA, l_reg, pa0, pa1, pa2, pa3); SBAR();
;     SLOAD(SO, (j + 2) * KVBLK); SBAR();
;     pv_d0(o, vb0, pa0, pa1, pa2, pa3); partialSM(pB0, pB1, m_reg, mnB, alB);
.LBB0_460:
	ds_read_b128 v[64:67], v191 offset:49152
	ds_read_b128 v[68:71], v191 offset:57344
	ds_read_b128 v[208:211], v192 offset:49152
	ds_read_b128 v[212:215], v192 offset:57344
	ds_read_b128 v[216:219], v193 offset:49152
	ds_read_b128 v[220:223], v193 offset:57344
	v_add_f32_e32 v161, 0, v175
	v_add_f32_e32 v161, v206, v161
	s_waitcnt lgkmcnt(5)
	v_mfma_f32_32x32x16_bf16 v[80:95], v[64:67], v[104:107], 0
	v_add_f32_e32 v161, v173, v161
	v_add_f32_e32 v161, v203, v161
	v_add_f32_e32 v161, v172, v161
	v_add_f32_e32 v161, v174, v161
	v_add_f32_e32 v161, v170, v161
	v_add_f32_e32 v161, v171, v161
	v_add_f32_e32 v161, v167, v161
	s_waitcnt lgkmcnt(4)
	v_mfma_f32_32x32x16_bf16 v[64:79], v[68:71], v[104:107], 0
	v_add_f32_e32 v161, v169, v161
	v_add_f32_e32 v161, v166, v161
	v_add_f32_e32 v161, v168, v161
	v_exp_f32_e32 v152, v152
	v_add_f32_e32 v161, v163, v161
	v_exp_f32_e32 v153, v153
	v_add_f32_e32 v161, v165, v161
	s_waitcnt lgkmcnt(3)
	v_mfma_f32_32x32x16_bf16 v[80:95], v[208:211], v[96:99], v[80:95]
	ds_read_b128 v[208:211], v194 offset:49152
	ds_read_b128 v[224:227], v194 offset:57344
	ds_read_b128 v[228:231], v195 offset:49152
	ds_read_b128 v[232:235], v195 offset:57344
	ds_read_b128 v[236:239], v196 offset:49152
	ds_read_b128 v[240:243], v196 offset:57344
	ds_read_b128 v[244:247], v197 offset:49152
	ds_read_b128 v[248:251], v197 offset:57344
	v_exp_f32_e32 v150, v150
	v_add_f32_e32 v161, v162, v161
	v_exp_f32_e32 v151, v151
	v_add_f32_e32 v161, v164, v161
	v_exp_f32_e32 v148, v148
	v_add_f32_e32 v161, v152, v161
	s_waitcnt lgkmcnt(10)
	v_mfma_f32_32x32x16_bf16 v[64:79], v[212:215], v[96:99], v[64:79]
	v_exp_f32_e32 v149, v149
	v_add_f32_e32 v161, v153, v161
	v_exp_f32_e32 v146, v146
	v_add_f32_e32 v161, v150, v161
	v_exp_f32_e32 v147, v147
	v_add_f32_e32 v161, v151, v161
	v_exp_f32_e32 v144, v144
	s_waitcnt lgkmcnt(9)
	v_mfma_f32_32x32x16_bf16 v[80:95], v[216:219], v[100:103], v[80:95]
	v_add_f32_e32 v161, v148, v161
	ds_read_b128 v[212:215], v198 offset:49152
	ds_read_b128 v[252:255], v198 offset:57344
	v_exp_f32_e32 v145, v145
	v_add_f32_e32 v161, v149, v161
	v_exp_f32_e32 v158, v158
	v_add_f32_e32 v161, v146, v161
	v_exp_f32_e32 v159, v159
	s_waitcnt lgkmcnt(10)
	v_mfma_f32_32x32x16_bf16 v[64:79], v[220:223], v[100:103], v[64:79]
	v_add_f32_e32 v161, v147, v161
	v_exp_f32_e32 v156, v156
	v_add_f32_e32 v161, v144, v161
	v_exp_f32_e32 v157, v157
	v_add_f32_e32 v161, v145, v161
	v_exp_f32_e32 v154, v154
	v_add_f32_e32 v161, v158, v161
	s_waitcnt lgkmcnt(9)
	v_mfma_f32_32x32x16_bf16 v[80:95], v[208:211], v[108:111], v[80:95]
	v_exp_f32_e32 v155, v155
	v_add_f32_e32 v161, v159, v161
	v_add_f32_e32 v161, v156, v161
	v_add_f32_e32 v161, v157, v161
	v_add_f32_e32 v161, v154, v161
	v_add_f32_e32 v200, v155, v161
	v_mov_b32_e32 v201, v200
	s_waitcnt lgkmcnt(8)
	v_mfma_f32_32x32x16_bf16 v[64:79], v[224:227], v[108:111], v[64:79]
	v_cvt_pk_bf16_f32 v202, v175, v206
	v_cvt_pk_bf16_f32 v203, v173, v203
	v_cvt_pk_bf16_f32 v204, v172, v174
	v_permlane32_swap_b32_e32 v200, v201
	v_cvt_pk_bf16_f32 v205, v170, v171
	v_permlane32_swap_b32_e32 v202, v204
	s_waitcnt lgkmcnt(7)
	v_mfma_f32_32x32x16_bf16 v[80:95], v[228:231], v[120:123], v[80:95]
	v_cvt_pk_bf16_f32 v170, v167, v169
	v_cvt_pk_bf16_f32 v171, v166, v168
	v_cvt_pk_bf16_f32 v172, v163, v165
	v_cvt_pk_bf16_f32 v173, v162, v164
	v_cvt_pk_bf16_f32 v162, v152, v153
	v_cvt_pk_bf16_f32 v163, v150, v151
	v_cvt_pk_bf16_f32 v164, v148, v149
	s_waitcnt lgkmcnt(6)
	v_mfma_f32_32x32x16_bf16 v[64:79], v[232:235], v[120:123], v[64:79]
	v_cvt_pk_bf16_f32 v165, v146, v147
	v_cvt_pk_bf16_f32 v166, v144, v145
	v_cvt_pk_bf16_f32 v167, v158, v159
	v_cvt_pk_bf16_f32 v168, v156, v157
	v_cvt_pk_bf16_f32 v169, v154, v155
	v_permlane32_swap_b32_e32 v203, v205
	s_waitcnt lgkmcnt(5)
	v_mfma_f32_32x32x16_bf16 v[80:95], v[236:239], v[124:127], v[80:95]
	v_permlane32_swap_b32_e32 v170, v172
	v_permlane32_swap_b32_e32 v171, v173
	v_permlane32_swap_b32_e32 v162, v164
	v_permlane32_swap_b32_e32 v163, v165
	s_waitcnt lgkmcnt(4)
	v_mfma_f32_32x32x16_bf16 v[64:79], v[240:243], v[124:127], v[64:79]
	v_permlane32_swap_b32_e32 v166, v168
	v_permlane32_swap_b32_e32 v167, v169
	s_waitcnt lgkmcnt(3)
	v_mfma_f32_32x32x16_bf16 v[80:95], v[244:247], v[112:115], v[80:95]
	s_waitcnt lgkmcnt(2)
	v_mfma_f32_32x32x16_bf16 v[64:79], v[248:251], v[112:115], v[64:79]
	s_waitcnt lgkmcnt(1)
	v_mfma_f32_32x32x16_bf16 v[80:95], v[212:215], v[116:119], v[80:95]
	s_waitcnt lgkmcnt(0)
	v_mfma_f32_32x32x16_bf16 v[64:79], v[252:255], v[116:119], v[64:79]
	ds_read_b64_tr_b16 v[206:207], v186 offset:0
	ds_read_b64_tr_b16 v[208:209], v186 offset:0x800
	ds_read_b64_tr_b16 v[210:211], v186 offset:0x1000
	ds_read_b64_tr_b16 v[212:213], v186 offset:0x1800
	ds_read_b64_tr_b16 v[214:215], v186 offset:0x2000
	ds_read_b64_tr_b16 v[216:217], v186 offset:0x2800
	ds_read_b64_tr_b16 v[218:219], v186 offset:0x3000
	ds_read_b64_tr_b16 v[220:221], v186 offset:0x3800
	v_add_co_u32_e32 v144, vcc, s75, v178
	s_nop 1
	v_addc_co_u32_e32 v145, vcc, -1, v179, vcc
	v_add_co_u32_e32 v148, vcc, s76, v178
	s_nop 1
	v_addc_co_u32_e32 v149, vcc, -1, v179, vcc
	v_add_co_u32_e32 v152, vcc, s77, v178
	global_load_dwordx4 v[144:147], v[144:145], off
	s_nop 0
	global_load_dwordx4 v[148:151], v[148:149], off
	v_addc_co_u32_e32 v153, vcc, -1, v179, vcc
	v_add_co_u32_e32 v156, vcc, s78, v178
	s_nop 1
	v_addc_co_u32_e32 v157, vcc, -1, v179, vcc
	global_load_dwordx4 v[152:155], v[152:153], off
	s_nop 0
	global_load_dwordx4 v[156:159], v[156:157], off
	s_waitcnt lgkmcnt(0)
; #define SBAR() __builtin_amdgcn_sched_barrier(0)
; __device__ __forceinline__ void partialSM(f32x16& p0, f32x16& p1, float& m_reg, float& mn, float& alpha) {
;   constexpr float C = SCALE * 1.4426950408889634f;
;   float pmax = p0[0]; for (int r = 1; r < 16; ++r) pmax = fmaxf(pmax, p0[r]); for (int r = 0; r < 16; ++r) pmax = fmaxf(pmax, p1[r]);
;   { auto rr = __builtin_amdgcn_permlane32_swap(__float_as_uint(pmax), __float_as_uint(pmax), false, false);
;     pmax = fmaxf(__uint_as_float(rr[0]), __uint_as_float(rr[1])); }
;   if (__builtin_expect(__all(pmax - m_reg <= THR / SCALE), 1)) { mn = m_reg; alpha = 1.f; }
;   else { mn = fmaxf(m_reg, pmax); alpha = __builtin_amdgcn_exp2f((m_reg - mn) * C); m_reg = mn; }
;   float mnC = -mn * C;
;   for (int r = 0; r < 16; ++r) p0[r] = fmaf(p0[r], C, mnC); for (int r = 0; r < 16; ++r) p1[r] = fmaf(p1[r], C, mnC);
;   for (int r = 0; r < 16; ++r) p0[r] = __builtin_amdgcn_exp2f(p0[r]);
; template <int D0> __device__ __forceinline__ void pv_one(f32x16& od, int vb, bf16x8 pa0, bf16x8 pa1, bf16x8 pa2, bf16x8 pa3) {
;   const s16x4 l0 = tr_read<v_rd_off(D0, 0, 0)>(vb), h0 = tr_read<v_rd_off(D0, 0, 1)>(vb), l1 = tr_read<v_rd_off(D0, 1, 0)>(vb), h1 = tr_read<v_rd_off(D0, 1, 1)>(vb);
;   const s16x4 l2 = tr_read<v_rd_off(D0, 2, 0)>(vb), h2 = tr_read<v_rd_off(D0, 2, 1)>(vb), l3 = tr_read<v_rd_off(D0, 3, 0)>(vb), h3 = tr_read<v_rd_off(D0, 3, 1)>(vb);
;   asm volatile("s_waitcnt lgkmcnt(0)" ::: "memory"); SBAR();
;     ...
;   od = __builtin_amdgcn_mfma_f32_32x32x16_bf16(pa0, PK(l0, h0), od, 0, 0, 0);
;   od = __builtin_amdgcn_mfma_f32_32x32x16_bf16(pa1, PK(l1, h1), od, 0, 0, 0);
;   od = __builtin_amdgcn_mfma_f32_32x32x16_bf16(pa2, PK(l2, h2), od, 0, 0, 0);
;   od = __builtin_amdgcn_mfma_f32_32x32x16_bf16(pa3, PK(l3, h3), od, 0, 0, 0);
;     ...
; }
; __device__ __forceinline__ void pv_d0(f32x16* o, int vb, bf16x8 pa0, bf16x8 pa1, bf16x8 pa2, bf16x8 pa3) {
;   pv_one<0>(o[0], vb, pa0, pa1, pa2, pa3); pv_one<1>(o[1], vb, pa0, pa1, pa2, pa3); pv_one<2>(o[2], vb, pa0, pa1, pa2, pa3); pv_one<3>(o[3], vb, pa0, pa1, pa2, pa3);
	s_nop 0
	v_mfma_f32_32x32x16_bf16 v[0:15], v[202:205], v[206:209], v[0:15]
	ds_read_b64_tr_b16 v[206:207], v186 offset:0x200
	ds_read_b64_tr_b16 v[208:209], v186 offset:0xa00
	v_mfma_f32_32x32x16_bf16 v[0:15], v[170:173], v[210:213], v[0:15]
	ds_read_b64_tr_b16 v[210:211], v186 offset:0x1200
	ds_read_b64_tr_b16 v[212:213], v186 offset:0x1a00
	v_mfma_f32_32x32x16_bf16 v[0:15], v[162:165], v[214:217], v[0:15]
	ds_read_b64_tr_b16 v[214:215], v186 offset:0x2200
	ds_read_b64_tr_b16 v[216:217], v186 offset:0x2a00
	ds_read_b64_tr_b16 v[222:223], v186 offset:0x3200
	ds_read_b64_tr_b16 v[224:225], v186 offset:0x3a00
	s_waitcnt lgkmcnt(0)
	v_mfma_f32_32x32x16_bf16 v[0:15], v[166:169], v[218:221], v[0:15]
	v_mfma_f32_32x32x16_bf16 v[48:63], v[202:205], v[206:209], v[48:63]
	ds_read_b64_tr_b16 v[206:207], v186 offset:0x400
	ds_read_b64_tr_b16 v[208:209], v186 offset:0xc00
	v_mfma_f32_32x32x16_bf16 v[48:63], v[170:173], v[210:213], v[48:63]
	ds_read_b64_tr_b16 v[210:211], v186 offset:0x1400
	ds_read_b64_tr_b16 v[212:213], v186 offset:0x1c00
	v_mfma_f32_32x32x16_bf16 v[48:63], v[162:165], v[214:217], v[48:63]
	ds_read_b64_tr_b16 v[214:215], v186 offset:0x2400
	ds_read_b64_tr_b16 v[216:217], v186 offset:0x2c00
	ds_read_b64_tr_b16 v[218:219], v186 offset:0x3400
	ds_read_b64_tr_b16 v[220:221], v186 offset:0x3c00
	s_waitcnt lgkmcnt(0)
	v_mfma_f32_32x32x16_bf16 v[48:63], v[166:169], v[222:225], v[48:63]
	v_mfma_f32_32x32x16_bf16 v[32:47], v[202:205], v[206:209], v[32:47]
	ds_read_b64_tr_b16 v[206:207], v186 offset:0x600
	ds_read_b64_tr_b16 v[208:209], v186 offset:0xe00
	v_mfma_f32_32x32x16_bf16 v[32:47], v[170:173], v[210:213], v[32:47]
	ds_read_b64_tr_b16 v[210:211], v186 offset:0x1600
	ds_read_b64_tr_b16 v[212:213], v186 offset:0x1e00
	v_mfma_f32_32x32x16_bf16 v[32:47], v[162:165], v[214:217], v[32:47]
	ds_read_b64_tr_b16 v[214:215], v186 offset:0x2600
	ds_read_b64_tr_b16 v[216:217], v186 offset:0x2e00
	ds_read_b64_tr_b16 v[222:223], v186 offset:0x3600
	ds_read_b64_tr_b16 v[224:225], v186 offset:0x3e00
	s_waitcnt lgkmcnt(0)
	v_mfma_f32_32x32x16_bf16 v[32:47], v[166:169], v[218:221], v[32:47]
	v_mfma_f32_32x32x16_bf16 v[16:31], v[202:205], v[206:209], v[16:31]
	v_max_f32_e32 v161, v81, v81
	v_max_f32_e32 v174, v80, v80
	v_max_f32_e32 v161, v174, v161
	v_max3_f32 v161, v161, v82, v83
	v_max3_f32 v161, v161, v84, v85
	v_max3_f32 v161, v161, v86, v87
	v_max3_f32 v161, v161, v88, v89
	v_max3_f32 v161, v161, v90, v91
	v_mfma_f32_32x32x16_bf16 v[16:31], v[170:173], v[210:213], v[16:31]
	v_max3_f32 v161, v161, v92, v93
	v_max3_f32 v161, v161, v94, v95
	v_max3_f32 v161, v161, v64, v65
	v_max3_f32 v161, v161, v66, v67
	v_max3_f32 v161, v161, v68, v69
	v_max3_f32 v161, v161, v70, v71
	v_max3_f32 v161, v161, v72, v73
	v_max3_f32 v161, v161, v74, v75
	v_mfma_f32_32x32x16_bf16 v[16:31], v[162:165], v[214:217], v[16:31]
	v_max3_f32 v161, v161, v76, v77
	v_max3_f32 v161, v161, v78, v79
	v_mov_b32_e32 v170, v161
	s_nop 1
	v_permlane32_swap_b32_e32 v161, v170
	v_max_f32_e32 v162, v170, v170
	v_max_f32_e32 v161, v161, v161
	v_max_f32_e32 v161, v161, v162
	v_max_f32_e32 v163, v160, v160
	v_sub_f32_e32 v162, v161, v160
	v_max_f32_e32 v161, v163, v161
	v_mfma_f32_32x32x16_bf16 v[16:31], v[166:169], v[222:225], v[16:31]
	v_sub_f32_e32 v163, v160, v161
	v_mul_f32_e32 v163, 0x3e0293ee, v163
	v_exp_f32_e32 v163, v163
	v_cmp_ge_f32_e32 vcc, s74, v162
	s_cmp_eq_u64 vcc, exec
	s_cselect_b64 s[4:5], -1, 0
	v_cndmask_b32_e64 v202, v163, 1.0, s[4:5]
	v_cmp_gt_f32_e32 vcc, 1.0, v202
	v_cndmask_b32_e64 v203, v161, v160, s[4:5]
	v_mul_f32_e32 v204, 0xbe0293ee, v203
	v_fmamk_f32 v80, v80, 0x3e0293ee, v204
	v_fmamk_f32 v81, v81, 0x3e0293ee, v204
	v_fmamk_f32 v82, v82, 0x3e0293ee, v204
	v_fmamk_f32 v83, v83, 0x3e0293ee, v204
	v_fmamk_f32 v84, v84, 0x3e0293ee, v204
	v_fmamk_f32 v85, v85, 0x3e0293ee, v204
	v_fmamk_f32 v86, v86, 0x3e0293ee, v204
	v_fmamk_f32 v87, v87, 0x3e0293ee, v204
	v_fmamk_f32 v88, v88, 0x3e0293ee, v204
	v_fmamk_f32 v89, v89, 0x3e0293ee, v204
	v_fmamk_f32 v90, v90, 0x3e0293ee, v204
	v_fmamk_f32 v91, v91, 0x3e0293ee, v204
	v_fmamk_f32 v92, v92, 0x3e0293ee, v204
	v_fmamk_f32 v93, v93, 0x3e0293ee, v204
	v_fmamk_f32 v94, v94, 0x3e0293ee, v204
	v_fmamk_f32 v95, v95, 0x3e0293ee, v204
	v_exp_f32_e32 v160, v80
	v_exp_f32_e32 v175, v81
	v_exp_f32_e32 v161, v82
	v_exp_f32_e32 v174, v83
	v_exp_f32_e32 v162, v84
	v_exp_f32_e32 v173, v85
	v_exp_f32_e32 v163, v86
	v_exp_f32_e32 v172, v87
	v_exp_f32_e32 v164, v88
	v_exp_f32_e32 v171, v89
	v_exp_f32_e32 v165, v90
	v_exp_f32_e32 v170, v91
	v_exp_f32_e32 v166, v92
	v_exp_f32_e32 v169, v93
	v_exp_f32_e32 v167, v94
	v_exp_f32_e32 v168, v95
	v_fmamk_f32 v213, v64, 0x3e0293ee, v204
	v_fmamk_f32 v214, v65, 0x3e0293ee, v204
	v_fmamk_f32 v215, v66, 0x3e0293ee, v204
	v_fmamk_f32 v216, v67, 0x3e0293ee, v204
	v_fmamk_f32 v217, v68, 0x3e0293ee, v204
	v_fmamk_f32 v206, v69, 0x3e0293ee, v204
	v_fmamk_f32 v207, v70, 0x3e0293ee, v204
	v_fmamk_f32 v208, v71, 0x3e0293ee, v204
	v_fmamk_f32 v209, v72, 0x3e0293ee, v204
	v_fmamk_f32 v210, v73, 0x3e0293ee, v204
	v_fmamk_f32 v211, v74, 0x3e0293ee, v204
	v_fmamk_f32 v212, v75, 0x3e0293ee, v204
	v_fmamk_f32 v205, v76, 0x3e0293ee, v204
	v_fmamk_f32 v218, v77, 0x3e0293ee, v204
	v_fmamk_f32 v219, v78, 0x3e0293ee, v204
	v_fmac_f32_e32 v204, 0x3e0293ee, v79
	s_barrier
	s_waitcnt vmcnt(4)
	s_waitcnt vmcnt(7)
	ds_write_b128 v187, v[128:131]
	s_waitcnt vmcnt(6)
	ds_write_b128 v188, v[136:139]
	s_waitcnt vmcnt(5)
	ds_write_b128 v189, v[132:135] offset:32768
	s_waitcnt vmcnt(4)
	ds_write_b128 v190, v[140:143] offset:32768
	s_cbranch_vccz .LBB0_464
; #define SBAR() __builtin_amdgcn_sched_barrier(0)
; #define SLOAD(i, k0) do { sr_[i].vs0 = St::ld8(&Vh[(long)((k0) + sr) * LDK + sc]); sr_[i].vs1 = St::ld8(&Vh[(long)((k0) + 32 + sr) * LDK + sc]); \
;     sr_[i].ks0 = St::ld8(&Kh[(long)((k0) + sr) * LDK + sc]); sr_[i].ks1 = St::ld8(&Kh[(long)((k0) + 32 + sr) * LDK + sc]); } while (0)
; #define RESC(a) do { if (__any((a) < 1.f)) { if (hi == 0) al_l[r32] = (a); asm volatile("s_waitcnt lgkmcnt(0)" ::: "memory"); \
;     for (int d = 0; d < 4; ++d) for (int r = 0; r < 16; ++r) o[d][r] *= al_l[crow(r, hi)]; } } while (0)
; __device__ __forceinline__ void attn_unit(const bf16* Qb, const bf16* __restrict__ Kh, const bf16* __restrict__ Vh, bf16* Ob, int seq, char* lds,
;                                           const float* __restrict__ rope, const float* __restrict__ qg, const int mk_wid) {
;     ...
;     RESC(alB); __syncthreads();
;     SBAR(); qkt(pA0, pA1, K_lds, qr, r32, hi);
;     finishSM(pB0, pB1, alB, l_reg, pa0, pa1, pa2, pa3); SBAR();
;     if (j + 3 < NT) SLOAD(SE, (j + 3) * KVBLK); SBAR();
;     pv_d0(o, vb0 + (int)SHM_V, pa0, pa1, pa2, pa3); partialSM(pA0, pA1, m_reg, mnA, alA);
	s_and_saveexec_b64 s[14:15], s[2:3]
	ds_write_b32 v183, v202 offset:128
	s_or_b64 exec, exec, s[14:15]
	s_waitcnt lgkmcnt(0)
	v_add_u32_e32 v80, s67, v176
	ds_read_b128 v[64:67], v80 offset:224
	ds_read_b128 v[68:71], v80 offset:192
	ds_read_b128 v[72:75], v80 offset:160
	ds_read_b128 v[76:79], v80 offset:128
	s_waitcnt lgkmcnt(3)
	v_pk_mul_f32 v[12:13], v[12:13], v[64:65]
	s_waitcnt lgkmcnt(2)
	v_pk_mul_f32 v[8:9], v[8:9], v[68:69]
	s_waitcnt lgkmcnt(1)
	v_pk_mul_f32 v[4:5], v[4:5], v[72:73]
	v_pk_mul_f32 v[14:15], v[14:15], v[66:67]
	v_pk_mul_f32 v[10:11], v[10:11], v[70:71]
	v_pk_mul_f32 v[6:7], v[6:7], v[74:75]
	s_waitcnt lgkmcnt(0)
	v_pk_mul_f32 v[2:3], v[2:3], v[78:79]
	v_pk_mul_f32 v[0:1], v[0:1], v[76:77]
	v_pk_mul_f32 v[60:61], v[60:61], v[64:65]
	v_pk_mul_f32 v[56:57], v[56:57], v[68:69]
	v_pk_mul_f32 v[52:53], v[52:53], v[72:73]
	v_pk_mul_f32 v[62:63], v[62:63], v[66:67]
	v_pk_mul_f32 v[58:59], v[58:59], v[70:71]
	v_pk_mul_f32 v[54:55], v[54:55], v[74:75]
	v_pk_mul_f32 v[50:51], v[50:51], v[78:79]
	v_pk_mul_f32 v[48:49], v[48:49], v[76:77]
	v_pk_mul_f32 v[44:45], v[44:45], v[64:65]
	v_pk_mul_f32 v[40:41], v[40:41], v[68:69]
	v_pk_mul_f32 v[36:37], v[36:37], v[72:73]
	v_pk_mul_f32 v[46:47], v[46:47], v[66:67]
	v_pk_mul_f32 v[42:43], v[42:43], v[70:71]
	v_pk_mul_f32 v[38:39], v[38:39], v[74:75]
	v_pk_mul_f32 v[34:35], v[34:35], v[78:79]
	v_pk_mul_f32 v[32:33], v[32:33], v[76:77]
	v_pk_mul_f32 v[28:29], v[28:29], v[64:65]
	v_pk_mul_f32 v[24:25], v[24:25], v[68:69]
	v_pk_mul_f32 v[20:21], v[20:21], v[72:73]
	v_pk_mul_f32 v[30:31], v[30:31], v[66:67]
	v_pk_mul_f32 v[26:27], v[26:27], v[70:71]
	v_pk_mul_f32 v[22:23], v[22:23], v[74:75]
	v_pk_mul_f32 v[18:19], v[18:19], v[78:79]
	v_pk_mul_f32 v[16:17], v[16:17], v[76:77]
.LBB0_464:
	s_waitcnt lgkmcnt(0)
	s_barrier
	ds_read_b128 v[64:67], v191 offset:32768
	ds_read_b128 v[68:71], v191 offset:40960
	ds_read_b128 v[220:223], v192 offset:32768
	ds_read_b128 v[224:227], v192 offset:40960
	v_exp_f32_e32 v213, v213
	v_exp_f32_e32 v214, v214
	s_waitcnt lgkmcnt(3)
	v_mfma_f32_32x32x16_bf16 v[80:95], v[64:67], v[104:107], 0
	v_exp_f32_e32 v215, v215
	v_exp_f32_e32 v216, v216
	v_exp_f32_e32 v217, v217
	v_exp_f32_e32 v206, v206
	v_exp_f32_e32 v207, v207
	v_exp_f32_e32 v208, v208
	v_exp_f32_e32 v209, v209
	s_waitcnt lgkmcnt(2)
	v_mfma_f32_32x32x16_bf16 v[64:79], v[68:71], v[104:107], 0
	v_exp_f32_e32 v210, v210
	v_exp_f32_e32 v211, v211
	v_exp_f32_e32 v212, v212
	v_exp_f32_e32 v218, v218
	v_exp_f32_e32 v219, v219
	s_waitcnt lgkmcnt(1)
	v_mfma_f32_32x32x16_bf16 v[80:95], v[220:223], v[96:99], v[80:95]
	s_waitcnt lgkmcnt(0)
	v_mfma_f32_32x32x16_bf16 v[64:79], v[224:227], v[96:99], v[64:79]
	ds_read_b128 v[220:223], v193 offset:32768
	ds_read_b128 v[224:227], v193 offset:40960
	s_waitcnt lgkmcnt(1)
	v_mfma_f32_32x32x16_bf16 v[80:95], v[220:223], v[100:103], v[80:95]
	s_waitcnt lgkmcnt(0)
	v_mfma_f32_32x32x16_bf16 v[64:79], v[224:227], v[100:103], v[64:79]
	ds_read_b128 v[220:223], v194 offset:32768
	ds_read_b128 v[224:227], v194 offset:40960
	s_waitcnt lgkmcnt(1)
	v_mfma_f32_32x32x16_bf16 v[80:95], v[220:223], v[108:111], v[80:95]
	s_waitcnt lgkmcnt(0)
	v_mfma_f32_32x32x16_bf16 v[64:79], v[224:227], v[108:111], v[64:79]
	ds_read_b128 v[220:223], v195 offset:32768
	ds_read_b128 v[224:227], v195 offset:40960
	s_waitcnt lgkmcnt(1)
	v_mfma_f32_32x32x16_bf16 v[80:95], v[220:223], v[120:123], v[80:95]
	s_waitcnt lgkmcnt(0)
	v_mfma_f32_32x32x16_bf16 v[64:79], v[224:227], v[120:123], v[64:79]
	ds_read_b128 v[220:223], v196 offset:32768
	ds_read_b128 v[224:227], v196 offset:40960
	s_waitcnt lgkmcnt(1)
	v_mfma_f32_32x32x16_bf16 v[80:95], v[220:223], v[124:127], v[80:95]
	s_waitcnt lgkmcnt(0)
	v_mfma_f32_32x32x16_bf16 v[64:79], v[224:227], v[124:127], v[64:79]
	ds_read_b128 v[220:223], v197 offset:32768
	ds_read_b128 v[224:227], v197 offset:40960
	s_waitcnt lgkmcnt(1)
	v_mfma_f32_32x32x16_bf16 v[80:95], v[220:223], v[112:115], v[80:95]
	s_waitcnt lgkmcnt(0)
	v_mfma_f32_32x32x16_bf16 v[64:79], v[224:227], v[112:115], v[64:79]
	ds_read_b128 v[220:223], v198 offset:32768
	ds_read_b128 v[224:227], v198 offset:40960
	s_waitcnt lgkmcnt(1)
	v_mfma_f32_32x32x16_bf16 v[80:95], v[220:223], v[116:119], v[80:95]
	v_exp_f32_e32 v221, v204
	v_add_f32_e32 v204, 0, v160
	v_add_f32_e32 v204, v175, v204
	v_add_f32_e32 v204, v161, v204
	v_add_f32_e32 v204, v174, v204
	v_add_f32_e32 v204, v162, v204
	v_add_f32_e32 v204, v173, v204
	v_add_f32_e32 v204, v163, v204
	v_add_f32_e32 v204, v172, v204
	v_add_f32_e32 v204, v164, v204
	v_add_f32_e32 v204, v171, v204
	v_add_f32_e32 v204, v165, v204
	v_add_f32_e32 v204, v170, v204
	v_add_f32_e32 v204, v166, v204
	v_add_f32_e32 v204, v169, v204
	v_add_f32_e32 v204, v167, v204
	v_add_f32_e32 v204, v168, v204
	v_add_f32_e32 v204, v213, v204
	v_add_f32_e32 v204, v214, v204
	v_add_f32_e32 v204, v215, v204
	v_add_f32_e32 v204, v216, v204
	v_add_f32_e32 v204, v217, v204
	v_add_f32_e32 v204, v206, v204
	v_add_f32_e32 v204, v207, v204
	v_add_f32_e32 v204, v208, v204
	v_exp_f32_e32 v220, v205
	v_add_f32_e32 v204, v209, v204
	v_add_f32_e32 v204, v210, v204
	s_waitcnt lgkmcnt(0)
	v_mfma_f32_32x32x16_bf16 v[64:79], v[224:227], v[116:119], v[64:79]
	v_add_f32_e32 v204, v211, v204
	v_add_f32_e32 v204, v212, v204
	v_add_f32_e32 v204, v220, v204
	v_add_f32_e32 v204, v218, v204
	v_add_f32_e32 v204, v219, v204
	v_add_f32_e32 v204, v221, v204
	v_mov_b32_e32 v205, v204
	v_cvt_pk_bf16_f32 v160, v160, v175
	v_cvt_pk_bf16_f32 v161, v161, v174
	v_cvt_pk_bf16_f32 v162, v162, v173
	v_cvt_pk_bf16_f32 v163, v163, v172
	v_cvt_pk_bf16_f32 v164, v164, v171
	v_cvt_pk_bf16_f32 v165, v165, v170
	v_cvt_pk_bf16_f32 v166, v166, v169
	v_cvt_pk_bf16_f32 v167, v167, v168
	v_cvt_pk_bf16_f32 v168, v213, v214
	v_cvt_pk_bf16_f32 v169, v215, v216
	v_cvt_pk_bf16_f32 v170, v217, v206
	v_cvt_pk_bf16_f32 v171, v207, v208
	v_cvt_pk_bf16_f32 v172, v209, v210
	v_cvt_pk_bf16_f32 v173, v211, v212
	v_cvt_pk_bf16_f32 v174, v220, v218
	v_cvt_pk_bf16_f32 v175, v219, v221
	s_nop 1
	v_permlane32_swap_b32_e32 v204, v205
	v_permlane32_swap_b32_e32 v160, v162
	v_permlane32_swap_b32_e32 v161, v163
	v_permlane32_swap_b32_e32 v164, v166
	v_permlane32_swap_b32_e32 v165, v167
	v_permlane32_swap_b32_e32 v168, v170
	v_permlane32_swap_b32_e32 v169, v171
	v_permlane32_swap_b32_e32 v172, v174
	v_permlane32_swap_b32_e32 v173, v175
	ds_read_b64_tr_b16 v[206:207], v185 offset:0
	ds_read_b64_tr_b16 v[208:209], v185 offset:0x800
	ds_read_b64_tr_b16 v[210:211], v185 offset:0x1000
	ds_read_b64_tr_b16 v[212:213], v185 offset:0x1800
	ds_read_b64_tr_b16 v[214:215], v185 offset:0x2000
	ds_read_b64_tr_b16 v[216:217], v185 offset:0x2800
	ds_read_b64_tr_b16 v[218:219], v185 offset:0x3000
	ds_read_b64_tr_b16 v[220:221], v185 offset:0x3800
	s_cmp_gt_u32 s80, 32
	s_cselect_b64 s[14:15], -1, 0
	s_and_b64 vcc, exec, s[14:15]
	s_cbranch_vccnz .LBB0_466
; #define SBAR() __builtin_amdgcn_sched_barrier(0)
; #define SLOAD(i, k0) do { sr_[i].vs0 = St::ld8(&Vh[(long)((k0) + sr) * LDK + sc]); sr_[i].vs1 = St::ld8(&Vh[(long)((k0) + 32 + sr) * LDK + sc]); \
;     sr_[i].ks0 = St::ld8(&Kh[(long)((k0) + sr) * LDK + sc]); sr_[i].ks1 = St::ld8(&Kh[(long)((k0) + 32 + sr) * LDK + sc]); } while (0)
; __device__ __forceinline__ void partialSM(f32x16& p0, f32x16& p1, float& m_reg, float& mn, float& alpha) {
;   constexpr float C = SCALE * 1.4426950408889634f;
;   float pmax = p0[0]; for (int r = 1; r < 16; ++r) pmax = fmaxf(pmax, p0[r]); for (int r = 0; r < 16; ++r) pmax = fmaxf(pmax, p1[r]);
;   { auto rr = __builtin_amdgcn_permlane32_swap(__float_as_uint(pmax), __float_as_uint(pmax), false, false);
;     pmax = fmaxf(__uint_as_float(rr[0]), __uint_as_float(rr[1])); }
;   if (__builtin_expect(__all(pmax - m_reg <= THR / SCALE), 1)) { mn = m_reg; alpha = 1.f; }
;   else { mn = fmaxf(m_reg, pmax); alpha = __builtin_amdgcn_exp2f((m_reg - mn) * C); m_reg = mn; }
;   float mnC = -mn * C;
;   for (int r = 0; r < 16; ++r) p0[r] = fmaf(p0[r], C, mnC); for (int r = 0; r < 16; ++r) p1[r] = fmaf(p1[r], C, mnC);
;   for (int r = 0; r < 16; ++r) p0[r] = __builtin_amdgcn_exp2f(p0[r]);
; __device__ __forceinline__ void attn_unit(const bf16* Qb, const bf16* __restrict__ Kh, const bf16* __restrict__ Vh, bf16* Ob, int seq, char* lds,
;                                           const float* __restrict__ rope, const float* __restrict__ qg, const int mk_wid) {
;     ...
;     if (j + 3 < NT) SLOAD(SE, (j + 3) * KVBLK); SBAR();
;     pv_d0(o, vb0 + (int)SHM_V, pa0, pa1, pa2, pa3); partialSM(pA0, pA1, m_reg, mnA, alA);
	v_add_co_u32_e32 v128, vcc, 0xffffc000, v178
	s_nop 1
	v_addc_co_u32_e32 v129, vcc, -1, v179, vcc
	v_add_co_u32_e32 v132, vcc, 0xfedfc000, v178
	s_nop 1
	v_addc_co_u32_e32 v133, vcc, -1, v179, vcc
	v_add_co_u32_e32 v140, vcc, 0xfee00000, v178
	global_load_dwordx4 v[128:131], v[128:129], off
	s_nop 0
	global_load_dwordx4 v[132:135], v[132:133], off
	v_addc_co_u32_e32 v141, vcc, -1, v179, vcc
	global_load_dwordx4 v[136:139], v[178:179], off
	s_nop 0
	global_load_dwordx4 v[140:143], v[140:141], off
.LBB0_466:
	s_waitcnt lgkmcnt(0)
	s_nop 0
	v_mfma_f32_32x32x16_bf16 v[0:15], v[160:163], v[206:209], v[0:15]
	ds_read_b64_tr_b16 v[206:207], v185 offset:0x200
	ds_read_b64_tr_b16 v[208:209], v185 offset:0xa00
	v_mfma_f32_32x32x16_bf16 v[0:15], v[164:167], v[210:213], v[0:15]
	ds_read_b64_tr_b16 v[210:211], v185 offset:0x1200
	ds_read_b64_tr_b16 v[212:213], v185 offset:0x1a00
	v_mfma_f32_32x32x16_bf16 v[0:15], v[168:171], v[214:217], v[0:15]
	ds_read_b64_tr_b16 v[214:215], v185 offset:0x2200
	ds_read_b64_tr_b16 v[216:217], v185 offset:0x2a00
	ds_read_b64_tr_b16 v[222:223], v185 offset:0x3200
	ds_read_b64_tr_b16 v[224:225], v185 offset:0x3a00
	s_waitcnt lgkmcnt(0)
	v_mfma_f32_32x32x16_bf16 v[0:15], v[172:175], v[218:221], v[0:15]
	v_mfma_f32_32x32x16_bf16 v[48:63], v[160:163], v[206:209], v[48:63]
	ds_read_b64_tr_b16 v[206:207], v185 offset:0x400
	ds_read_b64_tr_b16 v[208:209], v185 offset:0xc00
	v_mfma_f32_32x32x16_bf16 v[48:63], v[164:167], v[210:213], v[48:63]
	ds_read_b64_tr_b16 v[210:211], v185 offset:0x1400
	ds_read_b64_tr_b16 v[212:213], v185 offset:0x1c00
	v_mfma_f32_32x32x16_bf16 v[48:63], v[168:171], v[214:217], v[48:63]
	ds_read_b64_tr_b16 v[214:215], v185 offset:0x2400
	ds_read_b64_tr_b16 v[216:217], v185 offset:0x2c00
	ds_read_b64_tr_b16 v[218:219], v185 offset:0x3400
	ds_read_b64_tr_b16 v[220:221], v185 offset:0x3c00
	s_waitcnt lgkmcnt(0)
	v_mfma_f32_32x32x16_bf16 v[48:63], v[172:175], v[222:225], v[48:63]
	v_mfma_f32_32x32x16_bf16 v[32:47], v[160:163], v[206:209], v[32:47]
	ds_read_b64_tr_b16 v[206:207], v185 offset:0x600
	ds_read_b64_tr_b16 v[208:209], v185 offset:0xe00
	v_mfma_f32_32x32x16_bf16 v[32:47], v[164:167], v[210:213], v[32:47]
	ds_read_b64_tr_b16 v[210:211], v185 offset:0x1600
	ds_read_b64_tr_b16 v[212:213], v185 offset:0x1e00
	v_mfma_f32_32x32x16_bf16 v[32:47], v[168:171], v[214:217], v[32:47]
	ds_read_b64_tr_b16 v[214:215], v185 offset:0x2600
	ds_read_b64_tr_b16 v[216:217], v185 offset:0x2e00
	ds_read_b64_tr_b16 v[222:223], v185 offset:0x3600
	ds_read_b64_tr_b16 v[224:225], v185 offset:0x3e00
	s_waitcnt lgkmcnt(0)
	v_mfma_f32_32x32x16_bf16 v[32:47], v[172:175], v[218:221], v[32:47]
	v_mfma_f32_32x32x16_bf16 v[16:31], v[160:163], v[206:209], v[16:31]
	v_max_f32_e32 v218, v81, v81
	v_max_f32_e32 v219, v80, v80
	v_max_f32_e32 v218, v219, v218
	v_max3_f32 v218, v218, v82, v83
	v_max3_f32 v218, v218, v84, v85
	v_max3_f32 v160, v218, v86, v87
	v_max3_f32 v160, v160, v88, v89
	v_max3_f32 v160, v160, v90, v91
	v_mfma_f32_32x32x16_bf16 v[16:31], v[164:167], v[210:213], v[16:31]
	v_max3_f32 v160, v160, v92, v93
	v_max3_f32 v160, v160, v94, v95
	v_max3_f32 v160, v160, v64, v65
	v_max3_f32 v160, v160, v66, v67
	v_max3_f32 v160, v160, v68, v69
	v_max3_f32 v160, v160, v70, v71
	v_max3_f32 v160, v160, v72, v73
	v_max3_f32 v160, v160, v74, v75
	v_mfma_f32_32x32x16_bf16 v[16:31], v[168:171], v[214:217], v[16:31]
	v_max3_f32 v160, v160, v76, v77
	v_max3_f32 v160, v160, v78, v79
	v_mov_b32_e32 v161, v160
	s_nop 1
	v_permlane32_swap_b32_e32 v160, v161
	v_max_f32_e32 v161, v161, v161
	v_max_f32_e32 v160, v160, v160
	v_max_f32_e32 v160, v160, v161
	v_max_f32_e32 v162, v203, v203
	v_sub_f32_e32 v161, v160, v203
	v_max_f32_e32 v160, v162, v160
	v_mfma_f32_32x32x16_bf16 v[16:31], v[172:175], v[222:225], v[16:31]
	v_sub_f32_e32 v162, v203, v160
	v_mul_f32_e32 v162, 0x3e0293ee, v162
	v_exp_f32_e32 v162, v162
	v_cmp_ge_f32_e32 vcc, s74, v161
	s_cmp_eq_u64 vcc, exec
	s_cselect_b64 s[4:5], -1, 0
	v_cndmask_b32_e64 v161, v162, 1.0, s[4:5]
	v_cmp_gt_f32_e32 vcc, 1.0, v161
	v_cndmask_b32_e64 v160, v160, v203, s[4:5]
	v_mul_f32_e32 v254, 0xbe0293ee, v160
	v_mov_b32_e32 v255, v254
	v_fmamk_f32 v80, v80, 0x3e0293ee, v254
	v_fmamk_f32 v81, v81, 0x3e0293ee, v254
	v_fmamk_f32 v82, v82, 0x3e0293ee, v254
	v_fmamk_f32 v83, v83, 0x3e0293ee, v254
	v_fmamk_f32 v84, v84, 0x3e0293ee, v254
	v_fmamk_f32 v85, v85, 0x3e0293ee, v254
	v_fmamk_f32 v86, v86, 0x3e0293ee, v254
	v_fmamk_f32 v87, v87, 0x3e0293ee, v254
	v_fmamk_f32 v88, v88, 0x3e0293ee, v254
	v_fmamk_f32 v89, v89, 0x3e0293ee, v254
	v_fmamk_f32 v90, v90, 0x3e0293ee, v254
	v_fmamk_f32 v91, v91, 0x3e0293ee, v254
	v_fmamk_f32 v92, v92, 0x3e0293ee, v254
	v_fmamk_f32 v93, v93, 0x3e0293ee, v254
	v_fmamk_f32 v94, v94, 0x3e0293ee, v254
	v_fmac_f32_e32 v255, 0x3e0293ee, v95
	v_exp_f32_e32 v175, v80
	v_exp_f32_e32 v206, v81
	v_exp_f32_e32 v173, v82
	v_exp_f32_e32 v203, v83
	v_exp_f32_e32 v172, v84
	v_exp_f32_e32 v174, v85
	v_exp_f32_e32 v170, v86
	v_exp_f32_e32 v171, v87
	v_exp_f32_e32 v167, v88
	v_exp_f32_e32 v169, v89
	v_exp_f32_e32 v166, v90
	v_exp_f32_e32 v168, v91
	v_exp_f32_e32 v163, v92
	v_exp_f32_e32 v165, v93
	v_exp_f32_e32 v162, v94
	v_exp_f32_e32 v164, v255
	s_barrier
; #define SWAIT() do { asm volatile("s_waitcnt vmcnt(4)" ::: "memory"); } while (0)
; #define RESC(a) do { if (__any((a) < 1.f)) { if (hi == 0) al_l[r32] = (a); asm volatile("s_waitcnt lgkmcnt(0)" ::: "memory"); \
;     for (int d = 0; d < 4; ++d) for (int r = 0; r < 16; ++r) o[d][r] *= al_l[crow(r, hi)]; } } while (0)
; __device__ __forceinline__ void partialSM(f32x16& p0, f32x16& p1, float& m_reg, float& mn, float& alpha) {
;   constexpr float C = SCALE * 1.4426950408889634f;
;   float pmax = p0[0]; for (int r = 1; r < 16; ++r) pmax = fmaxf(pmax, p0[r]); for (int r = 0; r < 16; ++r) pmax = fmaxf(pmax, p1[r]);
;   { auto rr = __builtin_amdgcn_permlane32_swap(__float_as_uint(pmax), __float_as_uint(pmax), false, false);
;     pmax = fmaxf(__uint_as_float(rr[0]), __uint_as_float(rr[1])); }
;   if (__builtin_expect(__all(pmax - m_reg <= THR / SCALE), 1)) { mn = m_reg; alpha = 1.f; }
;   else { mn = fmaxf(m_reg, pmax); alpha = __builtin_amdgcn_exp2f((m_reg - mn) * C); m_reg = mn; }
;   float mnC = -mn * C;
;   for (int r = 0; r < 16; ++r) p0[r] = fmaf(p0[r], C, mnC); for (int r = 0; r < 16; ++r) p1[r] = fmaf(p1[r], C, mnC);
;   for (int r = 0; r < 16; ++r) p0[r] = __builtin_amdgcn_exp2f(p0[r]);
; __device__ __forceinline__ void attn_unit(const bf16* Qb, const bf16* __restrict__ Kh, const bf16* __restrict__ Vh, bf16* Ob, int seq, char* lds,
;                                           const float* __restrict__ rope, const float* __restrict__ qg, const int mk_wid) {
;     ...
;     pv_d0(o, vb0 + (int)SHM_V, pa0, pa1, pa2, pa3); partialSM(pA0, pA1, m_reg, mnA, alA);
;     __syncthreads(); SWAIT(); SWRITE(1, SO);
;     RESC(alA); __syncthreads();
	s_waitcnt vmcnt(4)
	s_waitcnt vmcnt(3)
	ds_write_b128 v187, v[144:147] offset:16384
	s_waitcnt vmcnt(2)
	ds_write_b128 v188, v[148:151] offset:16384
	s_waitcnt vmcnt(1)
	ds_write_b128 v189, v[152:155] offset:49152
	s_waitcnt vmcnt(0)
	ds_write_b128 v190, v[156:159] offset:49152
	s_cbranch_vccz .LBB0_470
	s_and_saveexec_b64 s[16:17], s[2:3]
	ds_write_b32 v183, v161 offset:128
	s_or_b64 exec, exec, s[16:17]
	s_waitcnt lgkmcnt(0)
	v_add_u32_e32 v156, s67, v176
	ds_read_b128 v[144:147], v156 offset:224
	ds_read_b128 v[148:151], v156 offset:192
	ds_read_b128 v[152:155], v156 offset:160
	ds_read_b128 v[156:159], v156 offset:128
	s_waitcnt lgkmcnt(3)
	v_pk_mul_f32 v[12:13], v[12:13], v[144:145]
	s_waitcnt lgkmcnt(2)
	v_pk_mul_f32 v[8:9], v[8:9], v[148:149]
	s_waitcnt lgkmcnt(1)
	v_pk_mul_f32 v[4:5], v[4:5], v[152:153]
	v_pk_mul_f32 v[14:15], v[14:15], v[146:147]
	v_pk_mul_f32 v[10:11], v[10:11], v[150:151]
	v_pk_mul_f32 v[6:7], v[6:7], v[154:155]
	s_waitcnt lgkmcnt(0)
	v_pk_mul_f32 v[2:3], v[2:3], v[158:159]
	v_pk_mul_f32 v[0:1], v[0:1], v[156:157]
	v_pk_mul_f32 v[60:61], v[60:61], v[144:145]
	v_pk_mul_f32 v[56:57], v[56:57], v[148:149]
	v_pk_mul_f32 v[52:53], v[52:53], v[152:153]
	v_pk_mul_f32 v[62:63], v[62:63], v[146:147]
	v_pk_mul_f32 v[58:59], v[58:59], v[150:151]
	v_pk_mul_f32 v[54:55], v[54:55], v[154:155]
	v_pk_mul_f32 v[50:51], v[50:51], v[158:159]
	v_pk_mul_f32 v[48:49], v[48:49], v[156:157]
	v_pk_mul_f32 v[44:45], v[44:45], v[144:145]
	v_pk_mul_f32 v[40:41], v[40:41], v[148:149]
	v_pk_mul_f32 v[36:37], v[36:37], v[152:153]
	v_pk_mul_f32 v[46:47], v[46:47], v[146:147]
	v_pk_mul_f32 v[42:43], v[42:43], v[150:151]
	v_pk_mul_f32 v[38:39], v[38:39], v[154:155]
	v_pk_mul_f32 v[34:35], v[34:35], v[158:159]
	v_pk_mul_f32 v[32:33], v[32:33], v[156:157]
	v_pk_mul_f32 v[28:29], v[28:29], v[144:145]
	v_pk_mul_f32 v[24:25], v[24:25], v[148:149]
	v_pk_mul_f32 v[20:21], v[20:21], v[152:153]
	v_pk_mul_f32 v[30:31], v[30:31], v[146:147]
	v_pk_mul_f32 v[26:27], v[26:27], v[150:151]
	v_pk_mul_f32 v[22:23], v[22:23], v[154:155]
	v_pk_mul_f32 v[18:19], v[18:19], v[158:159]
	v_pk_mul_f32 v[16:17], v[16:17], v[156:157]
.LBB0_470:
	v_mul_f32_e32 v154, 0xbe0293ee, v160
	v_pk_fma_f32 v[152:153], v[64:65], s[46:47], v[154:155] op_sel_hi:[1,0,0]
	v_add_f32_e32 v64, v200, v201
	v_fmac_f32_e32 v64, v199, v184
	v_add_f32_e32 v184, v204, v205
	v_pk_fma_f32 v[150:151], v[66:67], s[46:47], v[154:155] op_sel_hi:[1,0,0]
	v_pk_fma_f32 v[148:149], v[68:69], s[46:47], v[154:155] op_sel_hi:[1,0,0]
	v_pk_fma_f32 v[146:147], v[70:71], s[46:47], v[154:155] op_sel_hi:[1,0,0]
	v_pk_fma_f32 v[144:145], v[72:73], s[46:47], v[154:155] op_sel_hi:[1,0,0]
	v_pk_fma_f32 v[158:159], v[74:75], s[46:47], v[154:155] op_sel_hi:[1,0,0]
	v_pk_fma_f32 v[156:157], v[76:77], s[46:47], v[154:155] op_sel_hi:[1,0,0]
	v_pk_fma_f32 v[154:155], v[78:79], s[46:47], v[154:155] op_sel_hi:[1,0,0]
	v_fmac_f32_e32 v184, v64, v202
	s_add_i32 s80, s80, 2
	v_lshl_add_u64 v[178:179], v[178:179], 0, s[52:53]
	s_and_b64 vcc, exec, s[14:15]
	s_waitcnt lgkmcnt(0)
	s_barrier
	s_cbranch_vccnz .LBB0_472
	v_mov_b32_e32 v199, v161
	s_branch .LBB0_460
